# MLA fast loop: one barrier per key tile with three LDS stages (waves 0-3 QK,PV,barrier; waves 4-7 QK,barrier,PV), tile t+1 written during QK(t), loads one iteration ahead
# baseline (speedup 1.0000x reference)
.LBB0_821:
	v_mov_b32_e32 v101, v1
	s_waitcnt lgkmcnt(0)
	v_add_f32_e32 v1, v102, v105
	v_fmamk_f32 v1, v1, 0x3c2aaaab, v157
	v_mul_f32_e32 v102, 0x4b800000, v1
	v_cmp_gt_f32_e32 vcc, s41, v1
	v_mov_b32_e32 v123, v133
	v_mov_b32_e32 v109, v103
	v_cndmask_b32_e32 v1, v1, v102, vcc
	v_rsq_f32_e32 v1, v1
	v_mov_b32_e32 v121, v131
	v_mov_b32_e32 v105, v127
	v_mov_b32_e32 v119, v155
	v_mul_f32_e32 v102, 0x45800000, v1
	v_cndmask_b32_e32 v1, v1, v102, vcc
	v_mul_f32_e32 v124, 0x3e16c740, v1
	v_pk_mul_f32 v[102:103], v[124:125], v[122:123] op_sel_hi:[0,1]
	s_waitcnt vmcnt(4)
	v_pk_mul_f32 v[62:63], v[62:63], v[102:103]
	v_mov_b32_e32 v99, v111
	v_cvt_pk_bf16_f32 v102, v62, v63
	v_pk_mul_f32 v[62:63], v[124:125], v[120:121] op_sel_hi:[0,1]
	v_pk_mul_f32 v[62:63], v[64:65], v[62:63]
	v_mov_b32_e32 v111, v181
	v_cvt_pk_bf16_f32 v103, v62, v63
	v_pk_mul_f32 v[62:63], v[124:125], v[104:105] op_sel_hi:[0,1]
	v_pk_mul_f32 v[58:59], v[58:59], v[62:63]
	v_mov_b32_e32 v95, v117
	v_cvt_pk_bf16_f32 v104, v58, v59
	v_pk_mul_f32 v[58:59], v[124:125], v[118:119] op_sel_hi:[0,1]
	v_pk_mul_f32 v[58:59], v[60:61], v[58:59]
	v_mov_b32_e32 v117, v183
	v_cvt_pk_bf16_f32 v105, v58, v59
	v_pk_mul_f32 v[58:59], v[124:125], v[110:111] op_sel_hi:[0,1]
	v_pk_mul_f32 v[54:55], v[54:55], v[58:59]
	v_mov_b32_e32 v107, v113
	v_cvt_pk_bf16_f32 v110, v54, v55
	v_pk_mul_f32 v[54:55], v[124:125], v[116:117] op_sel_hi:[0,1]
	v_mov_b32_e32 v113, v185
	v_pk_mul_f32 v[54:55], v[56:57], v[54:55]
	v_mov_b32_e32 v97, v115
	v_cvt_pk_bf16_f32 v111, v54, v55
	v_pk_mul_f32 v[54:55], v[124:125], v[112:113] op_sel_hi:[0,1]
	v_mov_b32_e32 v115, v187
	v_pk_mul_f32 v[50:51], v[50:51], v[54:55]
	s_lshl_b64 s[38:39], s[12:13], 3
	v_cvt_pk_bf16_f32 v112, v50, v51
	v_pk_mul_f32 v[50:51], v[124:125], v[114:115] op_sel_hi:[0,1]
	v_pk_mul_f32 v[50:51], v[52:53], v[50:51]
	s_or_b32 s0, s38, s49
	v_cvt_pk_bf16_f32 v113, v50, v51
	v_pk_mul_f32 v[50:51], v[124:125], v[98:99] op_sel_hi:[0,1]
	v_pk_mul_f32 v[46:47], v[46:47], v[50:51]
	s_mul_i32 s13, s39, 0xc0
	v_cvt_pk_bf16_f32 v98, v46, v47
	v_pk_mul_f32 v[46:47], v[124:125], v[108:109] op_sel_hi:[0,1]
	v_pk_mul_f32 v[46:47], v[46:47], v[48:49]
	s_mul_hi_u32 s15, s0, 0xc0
	v_cvt_pk_bf16_f32 v99, v46, v47
	v_pk_mul_f32 v[46:47], v[124:125], v[100:101] op_sel_hi:[0,1]
	v_pk_mul_f32 v[42:43], v[46:47], v[42:43]
	v_mov_b32_e32 v93, v125
	v_cvt_pk_bf16_f32 v100, v42, v43
	v_pk_mul_f32 v[42:43], v[124:125], v[106:107] op_sel_hi:[0,1]
	v_pk_mul_f32 v[42:43], v[42:43], v[44:45]
	s_add_i32 s15, s15, s13
	v_cvt_pk_bf16_f32 v101, v42, v43
	v_pk_mul_f32 v[42:43], v[124:125], v[96:97] op_sel_hi:[0,1]
	v_pk_mul_f32 v[38:39], v[42:43], v[38:39]
	s_mulk_i32 s0, 0xc0
	v_cvt_pk_bf16_f32 v106, v38, v39
	v_pk_mul_f32 v[38:39], v[124:125], v[94:95] op_sel_hi:[0,1]
	v_pk_mul_f32 v[38:39], v[38:39], v[40:41]
	s_add_u32 s38, s42, s0
	v_cvt_pk_bf16_f32 v107, v38, v39
	v_pk_mul_f32 v[38:39], v[124:125], v[92:93] op_sel_hi:[0,1]
	v_mov_b32_e32 v91, v179
	v_pk_mul_f32 v[34:35], v[38:39], v[34:35]
	s_addc_u32 s39, s43, s15
	s_lshl_b32 s0, s34, 1
	v_cvt_pk_bf16_f32 v108, v34, v35
	v_pk_mul_f32 v[34:35], v[124:125], v[90:91] op_sel_hi:[0,1]
	s_add_u32 s51, s46, s0
	s_mul_hi_i32 s35, s50, s14
	s_mul_i32 s34, s50, s14
	v_pk_mul_f32 v[34:35], v[34:35], v[36:37]
	s_addc_u32 s52, s47, 0
	s_ashr_i32 s15, s14, 31
	s_lshl_b64 s[34:35], s[34:35], 7
	v_cvt_pk_bf16_f32 v109, v34, v35
	v_pk_mul_f32 v[34:35], v[124:125], v[86:87] op_sel_hi:[0,1]
	v_mov_b32_e32 v36, v10
	v_mov_b32_e32 v37, v15
	s_add_u32 s34, s51, s34
	v_pk_mul_f32 v[54:55], v[34:35], v[36:37]
	v_lshl_add_u64 v[36:37], s[38:39], 0, v[146:147]
	s_addc_u32 s35, s52, s35
	v_pk_mul_f32 v[34:35], v[124:125], v[84:85] op_sel_hi:[0,1]
	v_mov_b32_e32 v15, v11
	v_lshl_add_u64 v[38:39], v[148:149], 1, v[36:37]
	v_lshl_add_u64 v[36:37], s[38:39], 0, v[150:151]
	v_mov_b32_e32 v173, v135
	v_pk_mul_f32 v[10:11], v[34:35], v[14:15]
	v_lshl_add_u64 v[34:35], s[38:39], 0, v[142:143]
	v_lshl_add_u64 v[46:47], v[152:153], 1, v[36:37]
	v_lshl_add_u64 v[50:51], s[34:35], 0, v[172:173]
	v_mad_i64_i32 v[36:37], s[34:35], s50, v154, 0
	v_lshl_add_u64 v[34:35], v[144:145], 1, v[34:35]
	v_lshl_add_u64 v[42:43], v[36:37], 1, v[50:51]
	v_mad_i64_i32 v[52:53], s[34:35], s50, v156, 0
	global_load_dwordx4 v[34:37], v[34:35], off
	s_nop 0
	global_load_dwordx4 v[38:41], v[38:39], off
	s_nop 0
	global_load_dwordx4 v[42:45], v[42:43], off
	s_nop 0
	global_load_dwordx4 v[46:49], v[46:47], off
	v_lshl_add_u64 v[50:51], v[52:53], 1, v[50:51]
	global_load_dwordx4 v[50:53], v[50:51], off
	s_waitcnt vmcnt(5)
	v_mov_b32_e32 v88, v31
	v_mov_b32_e32 v89, v32
	v_mov_b32_e32 v77, v129
	v_mov_b32_e32 v57, v32
	v_mov_b32_e32 v58, v10
	v_mov_b32_e32 v59, v55
	v_mov_b32_e32 v32, v31
	v_mov_b32_e32 v31, v33
	v_mov_b32_e32 v15, v11
	v_mov_b32_e32 v56, v30
	v_pk_mul_f32 v[58:59], v[58:59], v[32:33]
	v_pk_mul_f32 v[10:11], v[10:11], v[30:31]
	v_pk_mul_f32 v[30:31], v[124:125], v[76:77] op_sel_hi:[0,1]
	v_mov_b32_e32 v32, v12
	v_mov_b32_e32 v33, v17
	v_pk_mul_f32 v[30:31], v[30:31], v[32:33]
	v_pk_mul_f32 v[32:33], v[124:125], v[74:75] op_sel_hi:[0,1]
	v_mov_b32_e32 v17, v13
	v_pk_mul_f32 v[12:13], v[32:33], v[16:17]
	v_mov_b32_e32 v82, v27
	v_mov_b32_e32 v83, v28
	v_mov_b32_e32 v73, v175
	v_mov_b32_e32 v14, v54
	v_pk_fma_f32 v[10:11], v[54:55], v[88:89], v[10:11]
	v_mov_b32_e32 v33, v28
	v_mov_b32_e32 v54, v12
	v_mov_b32_e32 v55, v31
	v_mov_b32_e32 v28, v27
	v_mov_b32_e32 v27, v29
	v_mov_b32_e32 v17, v13
	v_mov_b32_e32 v32, v26
	v_pk_mul_f32 v[54:55], v[54:55], v[28:29]
	v_pk_mul_f32 v[12:13], v[12:13], v[26:27]
	v_pk_mul_f32 v[26:27], v[124:125], v[72:73] op_sel_hi:[0,1]
	v_mov_b32_e32 v28, v2
	v_mov_b32_e32 v29, v7
	v_pk_mul_f32 v[26:27], v[26:27], v[28:29]
	v_pk_mul_f32 v[28:29], v[124:125], v[70:71] op_sel_hi:[0,1]
	v_mov_b32_e32 v7, v3
	v_pk_mul_f32 v[2:3], v[28:29], v[6:7]
	v_mov_b32_e32 v80, v23
	v_mov_b32_e32 v81, v24
	v_mov_b32_e32 v69, v177
	v_mov_b32_e32 v16, v30
	v_pk_fma_f32 v[12:13], v[30:31], v[82:83], v[12:13]
	v_mov_b32_e32 v29, v24
	v_mov_b32_e32 v30, v2
	v_mov_b32_e32 v31, v27
	v_mov_b32_e32 v24, v23
	v_mov_b32_e32 v23, v25
	v_mov_b32_e32 v7, v3
	v_mov_b32_e32 v28, v22
	v_pk_mul_f32 v[30:31], v[30:31], v[24:25]
	v_pk_mul_f32 v[2:3], v[2:3], v[22:23]
	v_pk_mul_f32 v[22:23], v[124:125], v[68:69] op_sel_hi:[0,1]
	v_mov_b32_e32 v24, v4
	v_mov_b32_e32 v25, v9
	v_pk_mul_f32 v[22:23], v[22:23], v[24:25]
	v_pk_mul_f32 v[24:25], v[124:125], v[66:67] op_sel_hi:[0,1]
	v_mov_b32_e32 v9, v5
	v_mov_b32_e32 v78, v19
	v_mov_b32_e32 v79, v20
	v_pk_mul_f32 v[4:5], v[24:25], v[8:9]
	v_mov_b32_e32 v25, v20
	v_mov_b32_e32 v20, v19
	v_mov_b32_e32 v19, v21
	v_mov_b32_e32 v6, v26
	v_pk_fma_f32 v[2:3], v[26:27], v[80:81], v[2:3]
	v_mov_b32_e32 v9, v5
	v_mov_b32_e32 v26, v4
	v_pk_mul_f32 v[4:5], v[4:5], v[18:19]
	s_lshl_b64 s[14:15], s[14:15], 7
	v_pk_fma_f32 v[4:5], v[22:23], v[78:79], v[4:5]
	v_cvt_pk_bf16_f32 v116, v2, v3
	v_lshl_add_u64 v[2:3], v[162:163], 0, s[14:15]
	v_cvt_pk_bf16_f32 v117, v4, v5
	v_mad_u64_u32 v[4:5], s[38:39], v2, s50, v[160:161]
	v_mad_i32_i24 v5, v3, s50, v5
	v_lshl_add_u64 v[2:3], v[164:165], 0, s[14:15]
	v_lshl_add_u64 v[174:175], v[4:5], 0, s[0:1]
	v_mad_u64_u32 v[4:5], s[14:15], v2, s50, v[160:161]
	v_mov_b32_e32 v27, v23
	v_mad_i32_i24 v5, v3, s50, v5
	v_mad_i64_i32 v[2:3], s[14:15], s12, v207, v[166:167]
	v_pk_fma_f32 v[16:17], v[16:17], v[32:33], v[54:55] neg_lo:[0,0,1] neg_hi:[0,0,1]
	v_mov_b32_e32 v8, v22
	v_mov_b32_e32 v24, v18
	v_pk_mul_f32 v[26:27], v[26:27], v[20:21]
	v_mad_u64_u32 v[178:179], s[14:15], s49, v206, v[2:3]
	v_mad_i64_i32 v[2:3], s[14:15], s12, v207, v[168:169]
	v_pk_fma_f32 v[14:15], v[14:15], v[56:57], v[58:59] neg_lo:[0,0,1] neg_hi:[0,0,1]
	v_pk_fma_f32 v[6:7], v[6:7], v[28:29], v[30:31] neg_lo:[0,0,1] neg_hi:[0,0,1]
	v_pk_fma_f32 v[8:9], v[8:9], v[24:25], v[26:27] neg_lo:[0,0,1] neg_hi:[0,0,1]
	v_cvt_pk_bf16_f32 v119, v16, v17
	v_add3_u32 v1, v201, v202, s44
	v_mad_u64_u32 v[180:181], s[14:15], s49, v206, v[2:3]
	v_mad_i64_i32 v[2:3], s[14:15], s12, v207, v[170:171]
	v_mov_b32_e32 v16, v135
	v_mov_b32_e32 v17, v135
	v_cvt_pk_bf16_f32 v118, v14, v15
	v_cvt_pk_bf16_f32 v120, v6, v7
	v_cvt_pk_bf16_f32 v121, v8, v9
	v_cvt_pk_bf16_f32 v114, v10, v11
	v_cvt_pk_bf16_f32 v115, v12, v13
	s_waitcnt vmcnt(4)
	ds_write_b128 v193, v[34:37]
	s_waitcnt vmcnt(3)
	ds_write_b128 v196, v[38:41]
	s_waitcnt vmcnt(1)
	ds_write_b128 v199, v[46:49]
	ds_write2_b64 v1, v[42:43], v[44:45] offset1:2
	v_add3_u32 v1, v201, v203, s44
	v_lshl_add_u64 v[176:177], v[4:5], 0, s[0:1]
	v_mad_u64_u32 v[182:183], s[14:15], s49, v206, v[2:3]
	v_mov_b32_e32 v2, v135
	v_mov_b32_e32 v3, v135
	v_mov_b32_e32 v4, v135
	v_mov_b32_e32 v5, v135
	v_mov_b32_e32 v6, v135
	v_mov_b32_e32 v7, v135
	v_mov_b32_e32 v8, v135
	v_mov_b32_e32 v9, v135
	v_mov_b32_e32 v10, v135
	v_mov_b32_e32 v11, v135
	v_mov_b32_e32 v12, v135
	v_mov_b32_e32 v13, v135
	v_mov_b32_e32 v14, v135
	v_mov_b32_e32 v15, v135
	v_mov_b64_e32 v[32:33], v[16:17]
	s_mov_b32 s13, 1
	s_lshr_b32 s34, s50, 7
	s_waitcnt vmcnt(0)
	ds_write2_b64 v1, v[50:51], v[52:53] offset1:2
	v_lshl_add_u64 v[236:237], s[78:79], 0, v[182:183]
	v_lshl_add_u64 v[238:239], s[78:79], 0, v[180:181]
	v_lshl_add_u64 v[240:241], s[78:79], 0, v[178:179]
	global_load_dwordx4 v[224:227], v[236:237], off
	global_load_dwordx4 v[228:231], v[238:239], off
	global_load_dwordx4 v[232:235], v[240:241], off
	v_lshl_add_u64 v[178:179], v[178:179], 0, s[8:9]
	v_lshl_add_u64 v[180:181], v[180:181], 0, s[8:9]
	v_lshl_add_u64 v[182:183], v[182:183], 0, s[8:9]
	v_mov_b32_e32 v133, 0xff800000
	v_mov_b32_e32 v1, 0
	v_mov_b64_e32 v[30:31], v[14:15]
	v_mov_b64_e32 v[28:29], v[12:13]
	v_mov_b64_e32 v[26:27], v[10:11]
	v_mov_b64_e32 v[24:25], v[8:9]
	v_mov_b64_e32 v[22:23], v[6:7]
	v_mov_b64_e32 v[20:21], v[4:5]
	v_mov_b64_e32 v[18:19], v[2:3]
	s_waitcnt lgkmcnt(0)
	s_barrier
	s_cmp_eq_u32 s100, 1
	s_cbranch_scc1 .Lmf_entry
	s_cmpk_lt_i32 s40, 0x100
	s_cbranch_scc1 .Lmla_noskew
	s_barrier
.Lmla_noskew:
.LBB0_822:
	s_setprio 0
	s_and_b32 s0, 1, s13
	s_cselect_b32 s12, 0, 0xac00
	s_cselect_b32 s0, 0xac00, 0
	s_add_i32 s12, s12, 0
	v_lshl_add_u64 v[248:249], s[98:99], 0, v[174:175]
	v_lshl_add_u64 v[250:251], s[98:99], 0, v[176:177]
	v_add3_u32 v236, s0, v191, v192
	v_add3_u32 v237, s0, v194, v195
	global_load_dwordx4 v[240:243], v[248:249], off offset:256
	global_load_dwordx4 v[244:247], v[250:251], off offset:256
	v_add3_u32 v238, s0, v197, v198
	v_add3_u32 v131, s12, v132, v204
	s_waitcnt vmcnt(2)
	ds_write_b128 v236, v[224:227]
	ds_write_b128 v237, v[228:231]
	ds_write_b128 v238, v[232:235]
	ds_read_b128 v[122:125], v131
	ds_read_b128 v[126:129], v131 offset:6656
	ds_read_b128 v[184:187], v131 offset:13312
	ds_read_b128 v[208:211], v131 offset:19968
	ds_read_b128 v[212:215], v131 offset:32
	ds_read_b128 v[216:219], v131 offset:6688
	s_waitcnt lgkmcnt(5)
	v_mfma_f32_32x32x16_bf16 v[82:97], v[122:125], v[102:105], 0
	ds_read_b128 v[122:125], v131 offset:13344
	s_waitcnt lgkmcnt(5)
	v_mfma_f32_32x32x16_bf16 v[66:81], v[126:129], v[102:105], 0
	ds_read_b128 v[126:129], v131 offset:20000
	s_waitcnt lgkmcnt(5)
	v_mfma_f32_32x32x16_bf16 v[50:65], v[184:187], v[102:105], 0
	ds_read_b128 v[184:187], v131 offset:64
	s_waitcnt lgkmcnt(5)
	v_mfma_f32_32x32x16_bf16 v[34:49], v[208:211], v[102:105], 0
	ds_read_b128 v[208:211], v131 offset:6720
	s_waitcnt lgkmcnt(5)
	v_mfma_f32_32x32x16_bf16 v[82:97], v[212:215], v[110:113], v[82:97]
	ds_read_b128 v[212:215], v131 offset:13376
	s_waitcnt lgkmcnt(5)
	v_mfma_f32_32x32x16_bf16 v[66:81], v[216:219], v[110:113], v[66:81]
	ds_read_b128 v[216:219], v131 offset:20032
	s_waitcnt lgkmcnt(5)
	v_mfma_f32_32x32x16_bf16 v[50:65], v[122:125], v[110:113], v[50:65]
	ds_read_b128 v[122:125], v131 offset:96
	s_waitcnt lgkmcnt(5)
	v_mfma_f32_32x32x16_bf16 v[34:49], v[126:129], v[110:113], v[34:49]
	ds_read_b128 v[126:129], v131 offset:6752
	s_waitcnt lgkmcnt(5)
	v_mfma_f32_32x32x16_bf16 v[82:97], v[184:187], v[98:101], v[82:97]
	ds_read_b128 v[184:187], v131 offset:13408
	s_waitcnt lgkmcnt(5)
	v_mfma_f32_32x32x16_bf16 v[66:81], v[208:211], v[98:101], v[66:81]
	ds_read_b128 v[208:211], v131 offset:20064
	s_waitcnt lgkmcnt(5)
	v_mfma_f32_32x32x16_bf16 v[50:65], v[212:215], v[98:101], v[50:65]
	ds_read_b128 v[212:215], v131 offset:128
	s_waitcnt lgkmcnt(5)
	v_mfma_f32_32x32x16_bf16 v[34:49], v[216:219], v[98:101], v[34:49]
	ds_read_b128 v[216:219], v131 offset:6784
	s_waitcnt lgkmcnt(5)
	v_mfma_f32_32x32x16_bf16 v[82:97], v[122:125], v[106:109], v[82:97]
	ds_read_b128 v[122:125], v131 offset:13440
	s_waitcnt lgkmcnt(5)
	v_mfma_f32_32x32x16_bf16 v[66:81], v[126:129], v[106:109], v[66:81]
	ds_read_b128 v[126:129], v131 offset:20096
	s_waitcnt lgkmcnt(5)
	v_mfma_f32_32x32x16_bf16 v[50:65], v[184:187], v[106:109], v[50:65]
	ds_read_b128 v[184:187], v131 offset:160
	s_waitcnt lgkmcnt(5)
	v_mfma_f32_32x32x16_bf16 v[34:49], v[208:211], v[106:109], v[34:49]
	ds_read_b128 v[208:211], v131 offset:6816
	s_waitcnt lgkmcnt(5)
	v_mfma_f32_32x32x16_bf16 v[82:97], v[212:215], v[118:121], v[82:97]
	ds_read_b128 v[212:215], v131 offset:13472
	s_waitcnt lgkmcnt(5)
	v_mfma_f32_32x32x16_bf16 v[66:81], v[216:219], v[118:121], v[66:81]
	ds_read_b128 v[216:219], v131 offset:20128
	s_waitcnt lgkmcnt(5)
	v_mfma_f32_32x32x16_bf16 v[50:65], v[122:125], v[118:121], v[50:65]
	s_waitcnt lgkmcnt(4)
	v_mfma_f32_32x32x16_bf16 v[34:49], v[126:129], v[118:121], v[34:49]
	s_waitcnt lgkmcnt(3)
	v_mfma_f32_32x32x16_bf16 v[82:97], v[184:187], v[114:117], v[82:97]
	s_waitcnt lgkmcnt(2)
	v_mfma_f32_32x32x16_bf16 v[66:81], v[208:211], v[114:117], v[66:81]
	s_waitcnt lgkmcnt(1)
	v_mfma_f32_32x32x16_bf16 v[50:65], v[212:215], v[114:117], v[50:65]
	s_waitcnt lgkmcnt(0)
	v_mfma_f32_32x32x16_bf16 v[34:49], v[216:219], v[114:117], v[34:49]
	s_nop 8
	v_max3_f32 v131, v82, s45, v83
	v_max3_f32 v131, v131, v84, v85
	v_max3_f32 v131, v131, v86, v87
	v_max3_f32 v239, v50, s45, v51
	v_max3_f32 v131, v131, v88, v89
	v_max3_f32 v239, v239, v52, v53
	v_max3_f32 v131, v131, v90, v91
	v_max3_f32 v239, v239, v54, v55
	v_max3_f32 v131, v131, v92, v93
	v_max3_f32 v239, v239, v56, v57
	v_max3_f32 v131, v131, v94, v95
	v_max3_f32 v239, v239, v58, v59
	v_max3_f32 v131, v131, v96, v97
	v_max3_f32 v239, v239, v60, v61
	v_max3_f32 v131, v131, v66, v67
	v_max3_f32 v239, v239, v62, v63
	v_max3_f32 v131, v131, v68, v69
	v_max3_f32 v239, v239, v64, v65
	v_max3_f32 v131, v131, v70, v71
	v_max3_f32 v239, v239, v34, v35
	v_max3_f32 v131, v131, v72, v73
	v_max3_f32 v239, v239, v36, v37
	v_max3_f32 v131, v131, v74, v75
	v_max3_f32 v239, v239, v38, v39
	v_max3_f32 v131, v131, v76, v77
	v_max3_f32 v239, v239, v40, v41
	v_max3_f32 v131, v131, v78, v79
	v_max3_f32 v239, v239, v42, v43
	v_max3_f32 v131, v131, v80, v81
	v_max3_f32 v239, v239, v44, v45
	v_max3_f32 v239, v239, v46, v47
	v_max3_f32 v239, v239, v48, v49
	v_max_f32_e32 v131, v131, v239
	ds_bpermute_b32 v155, v190, v131
	s_waitcnt lgkmcnt(0)
	v_max3_f32 v131, v133, v131, v155
	v_cmp_gt_f32_e32 vcc, v131, v133
	s_cbranch_vccz .LBB0_824
	v_sub_f32_e32 v133, v133, v131
	v_exp_f32_e32 v184, v133
	s_nop 0
	v_pk_mul_f32 v[32:33], v[32:33], v[184:185] op_sel_hi:[1,0]
	v_pk_mul_f32 v[30:31], v[30:31], v[184:185] op_sel_hi:[1,0]
	v_pk_mul_f32 v[28:29], v[28:29], v[184:185] op_sel_hi:[1,0]
	v_pk_mul_f32 v[26:27], v[26:27], v[184:185] op_sel_hi:[1,0]
	v_pk_mul_f32 v[24:25], v[24:25], v[184:185] op_sel_hi:[1,0]
	v_pk_mul_f32 v[22:23], v[22:23], v[184:185] op_sel_hi:[1,0]
	v_pk_mul_f32 v[20:21], v[20:21], v[184:185] op_sel_hi:[1,0]
	v_pk_mul_f32 v[18:19], v[18:19], v[184:185] op_sel_hi:[1,0]
	v_pk_mul_f32 v[16:17], v[16:17], v[184:185] op_sel_hi:[1,0]
	v_pk_mul_f32 v[14:15], v[14:15], v[184:185] op_sel_hi:[1,0]
	v_pk_mul_f32 v[12:13], v[12:13], v[184:185] op_sel_hi:[1,0]
	v_pk_mul_f32 v[10:11], v[10:11], v[184:185] op_sel_hi:[1,0]
	v_pk_mul_f32 v[8:9], v[8:9], v[184:185] op_sel_hi:[1,0]
	v_pk_mul_f32 v[6:7], v[6:7], v[184:185] op_sel_hi:[1,0]
	v_pk_mul_f32 v[4:5], v[4:5], v[184:185] op_sel_hi:[1,0]
	v_pk_mul_f32 v[2:3], v[2:3], v[184:185] op_sel_hi:[1,0]
	v_mul_f32_e32 v1, v1, v184

.Lmf_entry:
	v_mov_b32_e32 v239, 0
	v_lshl_add_u64 v[174:175], s[98:99], 0, v[174:175]
	v_lshl_add_u64 v[176:177], s[98:99], 0, v[176:177]
	v_lshl_add_u64 v[178:179], s[78:79], 0, v[178:179]
	v_lshl_add_u64 v[180:181], s[78:79], 0, v[180:181]
	v_lshl_add_u64 v[182:183], s[78:79], 0, v[182:183]
	s_mov_b32 s0, 0xac00
	global_load_dwordx4 v[240:243], v[174:175], off offset:256
	global_load_dwordx4 v[244:247], v[176:177], off offset:256
	v_add3_u32 v131, 0, v132, v204
	v_add3_u32 v173, 0, v189, v205
	v_add3_u32 v236, s0, v191, v192
	v_add3_u32 v237, s0, v194, v195
	v_add3_u32 v238, s0, v197, v198
	v_add_u32_e32 v220, s0, v200
	v_add_u32_e32 v155, 0x8900, v173
	v_add_u32_e32 v173, 0x6800, v173
	v_add3_u32 v221, v220, v202, s44
	v_add3_u32 v220, v220, v203, s44
	v_lshl_add_u64 v[174:175], v[174:175], 0, s[6:7]
	v_lshl_add_u64 v[176:177], v[176:177], 0, s[6:7]
	s_cmpk_lt_i32 s40, 0x100
	s_cbranch_scc0 .Lmfb_loop
.Lmfa_loop:
	s_setprio 0
	ds_read_b128 v[122:125], v131
	ds_read_b128 v[126:129], v131 offset:6656
	ds_read_b128 v[184:187], v131 offset:13312
	ds_read_b128 v[208:211], v131 offset:19968
	ds_read_b128 v[212:215], v131 offset:32
	ds_read_b128 v[216:219], v131 offset:6688
	s_waitcnt lgkmcnt(5)
	v_mfma_f32_32x32x16_bf16 v[82:97], v[122:125], v[102:105], 0
	ds_read_b128 v[122:125], v131 offset:13344
	s_waitcnt lgkmcnt(5)
	v_mfma_f32_32x32x16_bf16 v[66:81], v[126:129], v[102:105], 0
	ds_read_b128 v[126:129], v131 offset:20000
	s_waitcnt lgkmcnt(5)
	v_mfma_f32_32x32x16_bf16 v[50:65], v[184:187], v[102:105], 0
	ds_read_b128 v[184:187], v131 offset:64
	s_waitcnt lgkmcnt(5)
	v_mfma_f32_32x32x16_bf16 v[34:49], v[208:211], v[102:105], 0
	ds_read_b128 v[208:211], v131 offset:6720
	s_waitcnt lgkmcnt(5)
	v_mfma_f32_32x32x16_bf16 v[82:97], v[212:215], v[110:113], v[82:97]
	ds_read_b128 v[212:215], v131 offset:13376
	s_waitcnt lgkmcnt(5)
	v_mfma_f32_32x32x16_bf16 v[66:81], v[216:219], v[110:113], v[66:81]
	s_waitcnt vmcnt(0)
	ds_write_b128 v236, v[224:227]
	ds_write_b128 v237, v[228:231]
	ds_write_b128 v238, v[232:235]
	ds_write2_b64 v221, v[240:241], v[242:243] offset1:2
	ds_write2_b64 v220, v[244:245], v[246:247] offset1:2
	ds_read_b128 v[216:219], v131 offset:20032
	s_waitcnt lgkmcnt(10)
	v_mfma_f32_32x32x16_bf16 v[50:65], v[122:125], v[110:113], v[50:65]
	ds_read_b128 v[122:125], v131 offset:96
	s_waitcnt lgkmcnt(10)
	v_mfma_f32_32x32x16_bf16 v[34:49], v[126:129], v[110:113], v[34:49]
	global_load_dwordx4 v[224:227], v[182:183], off
	global_load_dwordx4 v[228:231], v[180:181], off
	global_load_dwordx4 v[232:235], v[178:179], off
	ds_read_b128 v[126:129], v131 offset:6752
	s_waitcnt lgkmcnt(10)
	v_mfma_f32_32x32x16_bf16 v[82:97], v[184:187], v[98:101], v[82:97]
	global_load_dwordx4 v[240:243], v[174:175], off offset:256
	global_load_dwordx4 v[244:247], v[176:177], off offset:256
	ds_read_b128 v[184:187], v131 offset:13408
	s_waitcnt lgkmcnt(10)
	v_mfma_f32_32x32x16_bf16 v[66:81], v[208:211], v[98:101], v[66:81]
	ds_read_b128 v[208:211], v131 offset:20064
	s_waitcnt lgkmcnt(10)
	v_mfma_f32_32x32x16_bf16 v[50:65], v[212:215], v[98:101], v[50:65]
	v_lshl_add_u64 v[174:175], v[174:175], 0, s[6:7]
	v_lshl_add_u64 v[176:177], v[176:177], 0, s[6:7]
	ds_read_b128 v[212:215], v131 offset:128
	s_waitcnt lgkmcnt(5)
	v_mfma_f32_32x32x16_bf16 v[34:49], v[216:219], v[98:101], v[34:49]
	v_lshl_add_u64 v[178:179], v[178:179], 0, s[8:9]
	v_lshl_add_u64 v[180:181], v[180:181], 0, s[8:9]
	v_lshl_add_u64 v[182:183], v[182:183], 0, s[8:9]
	ds_read_b128 v[216:219], v131 offset:6784
	s_waitcnt lgkmcnt(5)
	v_mfma_f32_32x32x16_bf16 v[82:97], v[122:125], v[106:109], v[82:97]
	ds_read_b128 v[122:125], v131 offset:13440
	s_waitcnt lgkmcnt(5)
	v_mfma_f32_32x32x16_bf16 v[66:81], v[126:129], v[106:109], v[66:81]
	ds_read_b128 v[126:129], v131 offset:20096
	s_waitcnt lgkmcnt(5)
	v_mfma_f32_32x32x16_bf16 v[50:65], v[184:187], v[106:109], v[50:65]
	ds_read_b128 v[184:187], v131 offset:160
	s_waitcnt lgkmcnt(5)
	v_mfma_f32_32x32x16_bf16 v[34:49], v[208:211], v[106:109], v[34:49]
	ds_read_b128 v[208:211], v131 offset:6816
	s_waitcnt lgkmcnt(5)
	v_mfma_f32_32x32x16_bf16 v[82:97], v[212:215], v[118:121], v[82:97]
	ds_read_b128 v[212:215], v131 offset:13472
	s_waitcnt lgkmcnt(5)
	v_mfma_f32_32x32x16_bf16 v[66:81], v[216:219], v[118:121], v[66:81]
	ds_read_b128 v[216:219], v131 offset:20128
	s_waitcnt lgkmcnt(5)
	v_mfma_f32_32x32x16_bf16 v[50:65], v[122:125], v[118:121], v[50:65]
	s_waitcnt lgkmcnt(4)
	v_mfma_f32_32x32x16_bf16 v[34:49], v[126:129], v[118:121], v[34:49]
	s_waitcnt lgkmcnt(3)
	v_mfma_f32_32x32x16_bf16 v[82:97], v[184:187], v[114:117], v[82:97]
	s_waitcnt lgkmcnt(2)
	v_mfma_f32_32x32x16_bf16 v[66:81], v[208:211], v[114:117], v[66:81]
	s_waitcnt lgkmcnt(1)
	v_mfma_f32_32x32x16_bf16 v[50:65], v[212:215], v[114:117], v[50:65]
	s_waitcnt lgkmcnt(0)
	v_mfma_f32_32x32x16_bf16 v[34:49], v[216:219], v[114:117], v[34:49]
	s_setprio 1
	ds_read_b128 v[122:125], v173
	ds_read_b128 v[126:129], v155 offset:256
	ds_read_b128 v[184:187], v173 offset:32
	ds_read_b128 v[208:211], v155 offset:288
	ds_read_b128 v[212:215], v173 offset:64
	ds_read_b128 v[216:219], v155 offset:320
	v_exp_f32_e32 v82, v82
	v_exp_f32_e32 v83, v83
	v_exp_f32_e32 v84, v84
	v_exp_f32_e32 v85, v85
	v_exp_f32_e32 v86, v86
	v_exp_f32_e32 v87, v87
	v_exp_f32_e32 v88, v88
	v_exp_f32_e32 v89, v89
	v_add_f32_e32 v1, v82, v1
	v_add_f32_e32 v239, v83, v239
	v_add_f32_e32 v1, v84, v1
	v_add_f32_e32 v239, v85, v239
	v_add_f32_e32 v1, v86, v1
	v_add_f32_e32 v239, v87, v239
	v_add_f32_e32 v1, v88, v1
	v_add_f32_e32 v239, v89, v239
	v_cvt_pk_bf16_f32 v82, v82, v83
	v_cvt_pk_bf16_f32 v83, v84, v85
	v_cvt_pk_bf16_f32 v84, v86, v87
	v_cvt_pk_bf16_f32 v85, v88, v89
	s_waitcnt lgkmcnt(4)
	v_exp_f32_e32 v90, v90
	v_exp_f32_e32 v91, v91
	v_exp_f32_e32 v92, v92
	v_exp_f32_e32 v93, v93
	v_mfma_f32_32x32x16_bf16 v[18:33], v[122:125], v[82:85], v[18:33]
	v_exp_f32_e32 v94, v94
	v_exp_f32_e32 v95, v95
	v_exp_f32_e32 v96, v96
	v_exp_f32_e32 v97, v97
	v_mfma_f32_32x32x16_bf16 v[2:17], v[126:129], v[82:85], v[2:17]
	ds_read_b128 v[122:125], v173 offset:96
	ds_read_b128 v[126:129], v155 offset:352
	v_add_f32_e32 v1, v90, v1
	v_add_f32_e32 v239, v91, v239
	v_add_f32_e32 v1, v92, v1
	v_add_f32_e32 v239, v93, v239
	v_add_f32_e32 v1, v94, v1
	v_add_f32_e32 v239, v95, v239
	v_add_f32_e32 v1, v96, v1
	v_add_f32_e32 v239, v97, v239
	v_cvt_pk_bf16_f32 v90, v90, v91
	v_cvt_pk_bf16_f32 v91, v92, v93
	v_cvt_pk_bf16_f32 v92, v94, v95
	v_cvt_pk_bf16_f32 v93, v96, v97
	s_waitcnt lgkmcnt(4)
	v_exp_f32_e32 v66, v66
	v_exp_f32_e32 v67, v67
	v_exp_f32_e32 v68, v68
	v_exp_f32_e32 v69, v69
	v_mfma_f32_32x32x16_bf16 v[18:33], v[184:187], v[90:93], v[18:33]
	v_exp_f32_e32 v70, v70
	v_exp_f32_e32 v71, v71
	v_exp_f32_e32 v72, v72
	v_exp_f32_e32 v73, v73
	v_mfma_f32_32x32x16_bf16 v[2:17], v[208:211], v[90:93], v[2:17]
	ds_read_b128 v[184:187], v173 offset:128
	ds_read_b128 v[208:211], v155 offset:384
	v_add_f32_e32 v1, v66, v1
	v_add_f32_e32 v239, v67, v239
	v_add_f32_e32 v1, v68, v1
	v_add_f32_e32 v239, v69, v239
	v_add_f32_e32 v1, v70, v1
	v_add_f32_e32 v239, v71, v239
	v_add_f32_e32 v1, v72, v1
	v_add_f32_e32 v239, v73, v239
	v_cvt_pk_bf16_f32 v66, v66, v67
	v_cvt_pk_bf16_f32 v67, v68, v69
	v_cvt_pk_bf16_f32 v68, v70, v71
	v_cvt_pk_bf16_f32 v69, v72, v73
	s_waitcnt lgkmcnt(4)
	v_exp_f32_e32 v74, v74
	v_exp_f32_e32 v75, v75
	v_exp_f32_e32 v76, v76
	v_exp_f32_e32 v77, v77
	v_mfma_f32_32x32x16_bf16 v[18:33], v[212:215], v[66:69], v[18:33]
	v_exp_f32_e32 v78, v78
	v_exp_f32_e32 v79, v79
	v_exp_f32_e32 v80, v80
	v_exp_f32_e32 v81, v81
	v_mfma_f32_32x32x16_bf16 v[2:17], v[216:219], v[66:69], v[2:17]
	ds_read_b128 v[212:215], v173 offset:160
	ds_read_b128 v[216:219], v155 offset:416
	v_add_f32_e32 v1, v74, v1
	v_add_f32_e32 v239, v75, v239
	v_add_f32_e32 v1, v76, v1
	v_add_f32_e32 v239, v77, v239
	v_add_f32_e32 v1, v78, v1
	v_add_f32_e32 v239, v79, v239
	v_add_f32_e32 v1, v80, v1
	v_add_f32_e32 v239, v81, v239
	v_cvt_pk_bf16_f32 v74, v74, v75
	v_cvt_pk_bf16_f32 v75, v76, v77
	v_cvt_pk_bf16_f32 v76, v78, v79
	v_cvt_pk_bf16_f32 v77, v80, v81
	s_waitcnt lgkmcnt(4)
	v_exp_f32_e32 v50, v50
	v_exp_f32_e32 v51, v51
	v_exp_f32_e32 v52, v52
	v_exp_f32_e32 v53, v53
	v_mfma_f32_32x32x16_bf16 v[18:33], v[122:125], v[74:77], v[18:33]
	v_exp_f32_e32 v54, v54
	v_exp_f32_e32 v55, v55
	v_exp_f32_e32 v56, v56
	v_exp_f32_e32 v57, v57
	v_mfma_f32_32x32x16_bf16 v[2:17], v[126:129], v[74:77], v[2:17]
	ds_read_b128 v[122:125], v173 offset:192
	ds_read_b128 v[126:129], v155 offset:448
	v_add_f32_e32 v1, v50, v1
	v_add_f32_e32 v239, v51, v239
	v_add_f32_e32 v1, v52, v1
	v_add_f32_e32 v239, v53, v239
	v_add_f32_e32 v1, v54, v1
	v_add_f32_e32 v239, v55, v239
	v_add_f32_e32 v1, v56, v1
	v_add_f32_e32 v239, v57, v239
	v_cvt_pk_bf16_f32 v50, v50, v51
	v_cvt_pk_bf16_f32 v51, v52, v53
	v_cvt_pk_bf16_f32 v52, v54, v55
	v_cvt_pk_bf16_f32 v53, v56, v57
	s_waitcnt lgkmcnt(4)
	v_exp_f32_e32 v58, v58
	v_exp_f32_e32 v59, v59
	v_exp_f32_e32 v60, v60
	v_exp_f32_e32 v61, v61
	v_mfma_f32_32x32x16_bf16 v[18:33], v[184:187], v[50:53], v[18:33]
	v_exp_f32_e32 v62, v62
	v_exp_f32_e32 v63, v63
	v_exp_f32_e32 v64, v64
	v_exp_f32_e32 v65, v65
	v_mfma_f32_32x32x16_bf16 v[2:17], v[208:211], v[50:53], v[2:17]
	ds_read_b128 v[184:187], v173 offset:224
	ds_read_b128 v[208:211], v155 offset:480
	v_add_f32_e32 v1, v58, v1
	v_add_f32_e32 v239, v59, v239
	v_add_f32_e32 v1, v60, v1
	v_add_f32_e32 v239, v61, v239
	v_add_f32_e32 v1, v62, v1
	v_add_f32_e32 v239, v63, v239
	v_add_f32_e32 v1, v64, v1
	v_add_f32_e32 v239, v65, v239
	v_cvt_pk_bf16_f32 v58, v58, v59
	v_cvt_pk_bf16_f32 v59, v60, v61
	v_cvt_pk_bf16_f32 v60, v62, v63
	v_cvt_pk_bf16_f32 v61, v64, v65
	s_waitcnt lgkmcnt(4)
	v_exp_f32_e32 v34, v34
	v_exp_f32_e32 v35, v35
	v_exp_f32_e32 v36, v36
	v_exp_f32_e32 v37, v37
	v_mfma_f32_32x32x16_bf16 v[18:33], v[212:215], v[58:61], v[18:33]
	v_exp_f32_e32 v38, v38
	v_exp_f32_e32 v39, v39
	v_exp_f32_e32 v40, v40
	v_exp_f32_e32 v41, v41
	v_mfma_f32_32x32x16_bf16 v[2:17], v[216:219], v[58:61], v[2:17]
	v_add_f32_e32 v1, v34, v1
	v_add_f32_e32 v239, v35, v239
	v_add_f32_e32 v1, v36, v1
	v_add_f32_e32 v239, v37, v239
	v_add_f32_e32 v1, v38, v1
	v_add_f32_e32 v239, v39, v239
	v_add_f32_e32 v1, v40, v1
	v_add_f32_e32 v239, v41, v239
	v_cvt_pk_bf16_f32 v34, v34, v35
	v_cvt_pk_bf16_f32 v35, v36, v37
	v_cvt_pk_bf16_f32 v36, v38, v39
	v_cvt_pk_bf16_f32 v37, v40, v41
	s_waitcnt lgkmcnt(2)
	v_exp_f32_e32 v42, v42
	v_exp_f32_e32 v43, v43
	v_exp_f32_e32 v44, v44
	v_exp_f32_e32 v45, v45
	v_mfma_f32_32x32x16_bf16 v[18:33], v[122:125], v[34:37], v[18:33]
	v_exp_f32_e32 v46, v46
	v_exp_f32_e32 v47, v47
	v_exp_f32_e32 v48, v48
	v_exp_f32_e32 v49, v49
	v_mfma_f32_32x32x16_bf16 v[2:17], v[126:129], v[34:37], v[2:17]
	v_add_f32_e32 v1, v42, v1
	v_add_f32_e32 v239, v43, v239
	v_add_f32_e32 v1, v44, v1
	v_add_f32_e32 v239, v45, v239
	v_add_f32_e32 v1, v46, v1
	v_add_f32_e32 v239, v47, v239
	v_add_f32_e32 v1, v48, v1
	v_add_f32_e32 v239, v49, v239
	v_cvt_pk_bf16_f32 v42, v42, v43
	v_cvt_pk_bf16_f32 v43, v44, v45
	v_cvt_pk_bf16_f32 v44, v46, v47
	v_cvt_pk_bf16_f32 v45, v48, v49
	s_waitcnt lgkmcnt(0)
	s_nop 0
	v_mfma_f32_32x32x16_bf16 v[18:33], v[184:187], v[42:45], v[18:33]
	v_mfma_f32_32x32x16_bf16 v[2:17], v[208:211], v[42:45], v[2:17]
	s_add_i32 s13, s13, 1
	s_add_i32 s101, s0, 0xac00
	s_cmp_eq_u32 s101, 0x20400
	s_cselect_b32 s101, 0, s101
	v_add3_u32 v131, s0, v132, v204
	v_add3_u32 v173, s0, v189, v205
	v_add3_u32 v236, s101, v191, v192
	v_add3_u32 v237, s101, v194, v195
	v_add3_u32 v238, s101, v197, v198
	v_add_u32_e32 v220, s101, v200
	v_add_u32_e32 v155, 0x8900, v173
	v_add_u32_e32 v173, 0x6800, v173
	v_add3_u32 v221, v220, v202, s44
	v_add3_u32 v220, v220, v203, s44
	s_cmp_eq_u32 s34, s13
	s_waitcnt lgkmcnt(0)
	s_barrier
	s_cbranch_scc1 .Lmfa_final
	s_mov_b32 s0, s101
	s_branch .Lmfa_loop
.Lmfb_loop:
	s_setprio 0
	ds_read_b128 v[122:125], v131
	ds_read_b128 v[126:129], v131 offset:6656
	ds_read_b128 v[184:187], v131 offset:13312
	ds_read_b128 v[208:211], v131 offset:19968
	ds_read_b128 v[212:215], v131 offset:32
	ds_read_b128 v[216:219], v131 offset:6688
	s_waitcnt lgkmcnt(5)
	v_mfma_f32_32x32x16_bf16 v[82:97], v[122:125], v[102:105], 0
	ds_read_b128 v[122:125], v131 offset:13344
	s_waitcnt lgkmcnt(5)
	v_mfma_f32_32x32x16_bf16 v[66:81], v[126:129], v[102:105], 0
	ds_read_b128 v[126:129], v131 offset:20000
	s_waitcnt lgkmcnt(5)
	v_mfma_f32_32x32x16_bf16 v[50:65], v[184:187], v[102:105], 0
	ds_read_b128 v[184:187], v131 offset:64
	s_waitcnt lgkmcnt(5)
	v_mfma_f32_32x32x16_bf16 v[34:49], v[208:211], v[102:105], 0
	ds_read_b128 v[208:211], v131 offset:6720
	s_waitcnt lgkmcnt(5)
	v_mfma_f32_32x32x16_bf16 v[82:97], v[212:215], v[110:113], v[82:97]
	ds_read_b128 v[212:215], v131 offset:13376
	s_waitcnt lgkmcnt(5)
	v_mfma_f32_32x32x16_bf16 v[66:81], v[216:219], v[110:113], v[66:81]
	s_waitcnt vmcnt(0)
	ds_write_b128 v236, v[224:227]
	ds_write_b128 v237, v[228:231]
	ds_write_b128 v238, v[232:235]
	ds_write2_b64 v221, v[240:241], v[242:243] offset1:2
	ds_write2_b64 v220, v[244:245], v[246:247] offset1:2
	ds_read_b128 v[216:219], v131 offset:20032
	s_waitcnt lgkmcnt(10)
	v_mfma_f32_32x32x16_bf16 v[50:65], v[122:125], v[110:113], v[50:65]
	ds_read_b128 v[122:125], v131 offset:96
	s_waitcnt lgkmcnt(10)
	v_mfma_f32_32x32x16_bf16 v[34:49], v[126:129], v[110:113], v[34:49]
	global_load_dwordx4 v[224:227], v[182:183], off
	global_load_dwordx4 v[228:231], v[180:181], off
	global_load_dwordx4 v[232:235], v[178:179], off
	ds_read_b128 v[126:129], v131 offset:6752
	s_waitcnt lgkmcnt(10)
	v_mfma_f32_32x32x16_bf16 v[82:97], v[184:187], v[98:101], v[82:97]
	global_load_dwordx4 v[240:243], v[174:175], off offset:256
	global_load_dwordx4 v[244:247], v[176:177], off offset:256
	ds_read_b128 v[184:187], v131 offset:13408
	s_waitcnt lgkmcnt(10)
	v_mfma_f32_32x32x16_bf16 v[66:81], v[208:211], v[98:101], v[66:81]
	ds_read_b128 v[208:211], v131 offset:20064
	s_waitcnt lgkmcnt(10)
	v_mfma_f32_32x32x16_bf16 v[50:65], v[212:215], v[98:101], v[50:65]
	v_lshl_add_u64 v[174:175], v[174:175], 0, s[6:7]
	v_lshl_add_u64 v[176:177], v[176:177], 0, s[6:7]
	ds_read_b128 v[212:215], v131 offset:128
	s_waitcnt lgkmcnt(5)
	v_mfma_f32_32x32x16_bf16 v[34:49], v[216:219], v[98:101], v[34:49]
	v_lshl_add_u64 v[178:179], v[178:179], 0, s[8:9]
	v_lshl_add_u64 v[180:181], v[180:181], 0, s[8:9]
	v_lshl_add_u64 v[182:183], v[182:183], 0, s[8:9]
	ds_read_b128 v[216:219], v131 offset:6784
	s_waitcnt lgkmcnt(5)
	v_mfma_f32_32x32x16_bf16 v[82:97], v[122:125], v[106:109], v[82:97]
	ds_read_b128 v[122:125], v131 offset:13440
	s_waitcnt lgkmcnt(5)
	v_mfma_f32_32x32x16_bf16 v[66:81], v[126:129], v[106:109], v[66:81]
	ds_read_b128 v[126:129], v131 offset:20096
	s_waitcnt lgkmcnt(5)
	v_mfma_f32_32x32x16_bf16 v[50:65], v[184:187], v[106:109], v[50:65]
	ds_read_b128 v[184:187], v131 offset:160
	s_waitcnt lgkmcnt(5)
	v_mfma_f32_32x32x16_bf16 v[34:49], v[208:211], v[106:109], v[34:49]
	ds_read_b128 v[208:211], v131 offset:6816
	s_waitcnt lgkmcnt(5)
	v_mfma_f32_32x32x16_bf16 v[82:97], v[212:215], v[118:121], v[82:97]
	ds_read_b128 v[212:215], v131 offset:13472
	s_waitcnt lgkmcnt(5)
	v_mfma_f32_32x32x16_bf16 v[66:81], v[216:219], v[118:121], v[66:81]
	ds_read_b128 v[216:219], v131 offset:20128
	s_waitcnt lgkmcnt(5)
	v_mfma_f32_32x32x16_bf16 v[50:65], v[122:125], v[118:121], v[50:65]
	s_waitcnt lgkmcnt(4)
	v_mfma_f32_32x32x16_bf16 v[34:49], v[126:129], v[118:121], v[34:49]
	s_waitcnt lgkmcnt(3)
	v_mfma_f32_32x32x16_bf16 v[82:97], v[184:187], v[114:117], v[82:97]
	s_waitcnt lgkmcnt(2)
	v_mfma_f32_32x32x16_bf16 v[66:81], v[208:211], v[114:117], v[66:81]
	s_waitcnt lgkmcnt(1)
	v_mfma_f32_32x32x16_bf16 v[50:65], v[212:215], v[114:117], v[50:65]
	s_waitcnt lgkmcnt(0)
	v_mfma_f32_32x32x16_bf16 v[34:49], v[216:219], v[114:117], v[34:49]
	s_barrier
	s_setprio 1
	ds_read_b128 v[122:125], v173
	ds_read_b128 v[126:129], v155 offset:256
	ds_read_b128 v[184:187], v173 offset:32
	ds_read_b128 v[208:211], v155 offset:288
	ds_read_b128 v[212:215], v173 offset:64
	ds_read_b128 v[216:219], v155 offset:320
	v_exp_f32_e32 v82, v82
	v_exp_f32_e32 v83, v83
	v_exp_f32_e32 v84, v84
	v_exp_f32_e32 v85, v85
	v_exp_f32_e32 v86, v86
	v_exp_f32_e32 v87, v87
	v_exp_f32_e32 v88, v88
	v_exp_f32_e32 v89, v89
	v_add_f32_e32 v1, v82, v1
	v_add_f32_e32 v239, v83, v239
	v_add_f32_e32 v1, v84, v1
	v_add_f32_e32 v239, v85, v239
	v_add_f32_e32 v1, v86, v1
	v_add_f32_e32 v239, v87, v239
	v_add_f32_e32 v1, v88, v1
	v_add_f32_e32 v239, v89, v239
	v_cvt_pk_bf16_f32 v82, v82, v83
	v_cvt_pk_bf16_f32 v83, v84, v85
	v_cvt_pk_bf16_f32 v84, v86, v87
	v_cvt_pk_bf16_f32 v85, v88, v89
	s_waitcnt lgkmcnt(4)
	v_exp_f32_e32 v90, v90
	v_exp_f32_e32 v91, v91
	v_exp_f32_e32 v92, v92
	v_exp_f32_e32 v93, v93
	v_mfma_f32_32x32x16_bf16 v[18:33], v[122:125], v[82:85], v[18:33]
	v_exp_f32_e32 v94, v94
	v_exp_f32_e32 v95, v95
	v_exp_f32_e32 v96, v96
	v_exp_f32_e32 v97, v97
	v_mfma_f32_32x32x16_bf16 v[2:17], v[126:129], v[82:85], v[2:17]
	ds_read_b128 v[122:125], v173 offset:96
	ds_read_b128 v[126:129], v155 offset:352
	v_add_f32_e32 v1, v90, v1
	v_add_f32_e32 v239, v91, v239
	v_add_f32_e32 v1, v92, v1
	v_add_f32_e32 v239, v93, v239
	v_add_f32_e32 v1, v94, v1
	v_add_f32_e32 v239, v95, v239
	v_add_f32_e32 v1, v96, v1
	v_add_f32_e32 v239, v97, v239
	v_cvt_pk_bf16_f32 v90, v90, v91
	v_cvt_pk_bf16_f32 v91, v92, v93
	v_cvt_pk_bf16_f32 v92, v94, v95
	v_cvt_pk_bf16_f32 v93, v96, v97
	s_waitcnt lgkmcnt(4)
	v_exp_f32_e32 v66, v66
	v_exp_f32_e32 v67, v67
	v_exp_f32_e32 v68, v68
	v_exp_f32_e32 v69, v69
	v_mfma_f32_32x32x16_bf16 v[18:33], v[184:187], v[90:93], v[18:33]
	v_exp_f32_e32 v70, v70
	v_exp_f32_e32 v71, v71
	v_exp_f32_e32 v72, v72
	v_exp_f32_e32 v73, v73
	v_mfma_f32_32x32x16_bf16 v[2:17], v[208:211], v[90:93], v[2:17]
	ds_read_b128 v[184:187], v173 offset:128
	ds_read_b128 v[208:211], v155 offset:384
	v_add_f32_e32 v1, v66, v1
	v_add_f32_e32 v239, v67, v239
	v_add_f32_e32 v1, v68, v1
	v_add_f32_e32 v239, v69, v239
	v_add_f32_e32 v1, v70, v1
	v_add_f32_e32 v239, v71, v239
	v_add_f32_e32 v1, v72, v1
	v_add_f32_e32 v239, v73, v239
	v_cvt_pk_bf16_f32 v66, v66, v67
	v_cvt_pk_bf16_f32 v67, v68, v69
	v_cvt_pk_bf16_f32 v68, v70, v71
	v_cvt_pk_bf16_f32 v69, v72, v73
	s_waitcnt lgkmcnt(4)
	v_exp_f32_e32 v74, v74
	v_exp_f32_e32 v75, v75
	v_exp_f32_e32 v76, v76
	v_exp_f32_e32 v77, v77
	v_mfma_f32_32x32x16_bf16 v[18:33], v[212:215], v[66:69], v[18:33]
	v_exp_f32_e32 v78, v78
	v_exp_f32_e32 v79, v79
	v_exp_f32_e32 v80, v80
	v_exp_f32_e32 v81, v81
	v_mfma_f32_32x32x16_bf16 v[2:17], v[216:219], v[66:69], v[2:17]
	ds_read_b128 v[212:215], v173 offset:160
	ds_read_b128 v[216:219], v155 offset:416
	v_add_f32_e32 v1, v74, v1
	v_add_f32_e32 v239, v75, v239
	v_add_f32_e32 v1, v76, v1
	v_add_f32_e32 v239, v77, v239
	v_add_f32_e32 v1, v78, v1
	v_add_f32_e32 v239, v79, v239
	v_add_f32_e32 v1, v80, v1
	v_add_f32_e32 v239, v81, v239
	v_cvt_pk_bf16_f32 v74, v74, v75
	v_cvt_pk_bf16_f32 v75, v76, v77
	v_cvt_pk_bf16_f32 v76, v78, v79
	v_cvt_pk_bf16_f32 v77, v80, v81
	s_waitcnt lgkmcnt(4)
	v_exp_f32_e32 v50, v50
	v_exp_f32_e32 v51, v51
	v_exp_f32_e32 v52, v52
	v_exp_f32_e32 v53, v53
	v_mfma_f32_32x32x16_bf16 v[18:33], v[122:125], v[74:77], v[18:33]
	v_exp_f32_e32 v54, v54
	v_exp_f32_e32 v55, v55
	v_exp_f32_e32 v56, v56
	v_exp_f32_e32 v57, v57
	v_mfma_f32_32x32x16_bf16 v[2:17], v[126:129], v[74:77], v[2:17]
	ds_read_b128 v[122:125], v173 offset:192
	ds_read_b128 v[126:129], v155 offset:448
	v_add_f32_e32 v1, v50, v1
	v_add_f32_e32 v239, v51, v239
	v_add_f32_e32 v1, v52, v1
	v_add_f32_e32 v239, v53, v239
	v_add_f32_e32 v1, v54, v1
	v_add_f32_e32 v239, v55, v239
	v_add_f32_e32 v1, v56, v1
	v_add_f32_e32 v239, v57, v239
	v_cvt_pk_bf16_f32 v50, v50, v51
	v_cvt_pk_bf16_f32 v51, v52, v53
	v_cvt_pk_bf16_f32 v52, v54, v55
	v_cvt_pk_bf16_f32 v53, v56, v57
	s_waitcnt lgkmcnt(4)
	v_exp_f32_e32 v58, v58
	v_exp_f32_e32 v59, v59
	v_exp_f32_e32 v60, v60
	v_exp_f32_e32 v61, v61
	v_mfma_f32_32x32x16_bf16 v[18:33], v[184:187], v[50:53], v[18:33]
	v_exp_f32_e32 v62, v62
	v_exp_f32_e32 v63, v63
	v_exp_f32_e32 v64, v64
	v_exp_f32_e32 v65, v65
	v_mfma_f32_32x32x16_bf16 v[2:17], v[208:211], v[50:53], v[2:17]
	ds_read_b128 v[184:187], v173 offset:224
	ds_read_b128 v[208:211], v155 offset:480
	v_add_f32_e32 v1, v58, v1
	v_add_f32_e32 v239, v59, v239
	v_add_f32_e32 v1, v60, v1
	v_add_f32_e32 v239, v61, v239
	v_add_f32_e32 v1, v62, v1
	v_add_f32_e32 v239, v63, v239
	v_add_f32_e32 v1, v64, v1
	v_add_f32_e32 v239, v65, v239
	v_cvt_pk_bf16_f32 v58, v58, v59
	v_cvt_pk_bf16_f32 v59, v60, v61
	v_cvt_pk_bf16_f32 v60, v62, v63
	v_cvt_pk_bf16_f32 v61, v64, v65
	s_waitcnt lgkmcnt(4)
	v_exp_f32_e32 v34, v34
	v_exp_f32_e32 v35, v35
	v_exp_f32_e32 v36, v36
	v_exp_f32_e32 v37, v37
	v_mfma_f32_32x32x16_bf16 v[18:33], v[212:215], v[58:61], v[18:33]
	v_exp_f32_e32 v38, v38
	v_exp_f32_e32 v39, v39
	v_exp_f32_e32 v40, v40
	v_exp_f32_e32 v41, v41
	v_mfma_f32_32x32x16_bf16 v[2:17], v[216:219], v[58:61], v[2:17]
	v_add_f32_e32 v1, v34, v1
	v_add_f32_e32 v239, v35, v239
	v_add_f32_e32 v1, v36, v1
	v_add_f32_e32 v239, v37, v239
	v_add_f32_e32 v1, v38, v1
	v_add_f32_e32 v239, v39, v239
	v_add_f32_e32 v1, v40, v1
	v_add_f32_e32 v239, v41, v239
	v_cvt_pk_bf16_f32 v34, v34, v35
	v_cvt_pk_bf16_f32 v35, v36, v37
	v_cvt_pk_bf16_f32 v36, v38, v39
	v_cvt_pk_bf16_f32 v37, v40, v41
	s_waitcnt lgkmcnt(2)
	v_exp_f32_e32 v42, v42
	v_exp_f32_e32 v43, v43
	v_exp_f32_e32 v44, v44
	v_exp_f32_e32 v45, v45
	v_mfma_f32_32x32x16_bf16 v[18:33], v[122:125], v[34:37], v[18:33]
	v_exp_f32_e32 v46, v46
	v_exp_f32_e32 v47, v47
	v_exp_f32_e32 v48, v48
	v_exp_f32_e32 v49, v49
	v_mfma_f32_32x32x16_bf16 v[2:17], v[126:129], v[34:37], v[2:17]
	v_add_f32_e32 v1, v42, v1
	v_add_f32_e32 v239, v43, v239
	v_add_f32_e32 v1, v44, v1
	v_add_f32_e32 v239, v45, v239
	v_add_f32_e32 v1, v46, v1
	v_add_f32_e32 v239, v47, v239
	v_add_f32_e32 v1, v48, v1
	v_add_f32_e32 v239, v49, v239
	v_cvt_pk_bf16_f32 v42, v42, v43
	v_cvt_pk_bf16_f32 v43, v44, v45
	v_cvt_pk_bf16_f32 v44, v46, v47
	v_cvt_pk_bf16_f32 v45, v48, v49
	s_waitcnt lgkmcnt(0)
	s_nop 0
	v_mfma_f32_32x32x16_bf16 v[18:33], v[184:187], v[42:45], v[18:33]
	v_mfma_f32_32x32x16_bf16 v[2:17], v[208:211], v[42:45], v[2:17]
	s_add_i32 s13, s13, 1
	s_add_i32 s101, s0, 0xac00
	s_cmp_eq_u32 s101, 0x20400
	s_cselect_b32 s101, 0, s101
	v_add3_u32 v131, s0, v132, v204
	v_add3_u32 v173, s0, v189, v205
	v_add3_u32 v236, s101, v191, v192
	v_add3_u32 v237, s101, v194, v195
	v_add3_u32 v238, s101, v197, v198
	v_add_u32_e32 v220, s101, v200
	v_add_u32_e32 v155, 0x8900, v173
	v_add_u32_e32 v173, 0x6800, v173
	v_add3_u32 v221, v220, v202, s44
	v_add3_u32 v220, v220, v203, s44
	s_cmp_eq_u32 s34, s13
	s_cbranch_scc1 .Lmfb_final
	s_mov_b32 s0, s101
	s_branch .Lmfb_loop
.Lmfa_final:
	s_setprio 0
	v_add_f32_e32 v1, v1, v239
	v_add3_u32 v133, s0, v132, v204
	ds_read_b128 v[34:37], v133
	ds_read_b128 v[122:125], v133 offset:32
	s_waitcnt lgkmcnt(1)
	v_mfma_f32_32x32x16_bf16 v[82:97], v[34:37], v[102:105], 0
	ds_read_b128 v[34:37], v133 offset:6656
	ds_read_b128 v[126:129], v133 offset:6688
	s_waitcnt lgkmcnt(1)
	v_mfma_f32_32x32x16_bf16 v[66:81], v[34:37], v[102:105], 0
	ds_read_b128 v[34:37], v133 offset:13312
	ds_read_b128 v[174:177], v133 offset:13344
	s_waitcnt lgkmcnt(1)
	v_mfma_f32_32x32x16_bf16 v[50:65], v[34:37], v[102:105], 0
	ds_read_b128 v[34:37], v133 offset:19968
	ds_read_b128 v[178:181], v133 offset:20000
	s_waitcnt lgkmcnt(1)
	v_mfma_f32_32x32x16_bf16 v[34:49], v[34:37], v[102:105], 0
	v_mfma_f32_32x32x16_bf16 v[82:97], v[122:125], v[110:113], v[82:97]
	v_mfma_f32_32x32x16_bf16 v[66:81], v[126:129], v[110:113], v[66:81]
	v_mfma_f32_32x32x16_bf16 v[50:65], v[174:177], v[110:113], v[50:65]
	s_waitcnt lgkmcnt(0)
	v_mfma_f32_32x32x16_bf16 v[34:49], v[178:181], v[110:113], v[34:49]
	ds_read_b128 v[102:105], v133 offset:64
	ds_read_b128 v[110:113], v133 offset:96
	s_waitcnt lgkmcnt(1)
	v_mfma_f32_32x32x16_bf16 v[82:97], v[102:105], v[98:101], v[82:97]
	ds_read_b128 v[102:105], v133 offset:6720
	ds_read_b128 v[122:125], v133 offset:6752
	s_waitcnt lgkmcnt(1)
	v_mfma_f32_32x32x16_bf16 v[66:81], v[102:105], v[98:101], v[66:81]
	ds_read_b128 v[102:105], v133 offset:13376
	ds_read_b128 v[126:129], v133 offset:13408
	s_waitcnt lgkmcnt(1)
	v_mfma_f32_32x32x16_bf16 v[50:65], v[102:105], v[98:101], v[50:65]
	ds_read_b128 v[102:105], v133 offset:20032
	ds_read_b128 v[174:177], v133 offset:20064
	v_mfma_f32_32x32x16_bf16 v[82:97], v[110:113], v[106:109], v[82:97]
	s_waitcnt lgkmcnt(1)
	v_mfma_f32_32x32x16_bf16 v[34:49], v[102:105], v[98:101], v[34:49]
	ds_read_b128 v[98:101], v133 offset:128
	ds_read_b128 v[102:105], v133 offset:160
	v_mfma_f32_32x32x16_bf16 v[66:81], v[122:125], v[106:109], v[66:81]
	s_waitcnt lgkmcnt(1)
	v_mfma_f32_32x32x16_bf16 v[82:97], v[98:101], v[118:121], v[82:97]
	v_mfma_f32_32x32x16_bf16 v[50:65], v[126:129], v[106:109], v[50:65]
	v_mfma_f32_32x32x16_bf16 v[34:49], v[174:177], v[106:109], v[34:49]
	ds_read_b128 v[98:101], v133 offset:6784
	ds_read_b128 v[106:109], v133 offset:6816
	s_waitcnt lgkmcnt(1)
	v_mfma_f32_32x32x16_bf16 v[66:81], v[98:101], v[118:121], v[66:81]
	ds_read_b128 v[98:101], v133 offset:13440
	ds_read_b128 v[110:113], v133 offset:13472
	v_mfma_f32_32x32x16_bf16 v[82:97], v[102:105], v[114:117], v[82:97]
	s_waitcnt lgkmcnt(1)
	v_mfma_f32_32x32x16_bf16 v[50:65], v[98:101], v[118:121], v[50:65]
	s_nop 9
	ds_read_b128 v[98:101], v133 offset:20096
	ds_read_b128 v[102:105], v133 offset:20128
	v_mfma_f32_32x32x16_bf16 v[66:81], v[106:109], v[114:117], v[66:81]
	s_nop 6
	s_waitcnt lgkmcnt(2)
	v_mfma_f32_32x32x16_bf16 v[50:65], v[110:113], v[114:117], v[50:65]
	s_waitcnt lgkmcnt(1)
	v_mfma_f32_32x32x16_bf16 v[34:49], v[98:101], v[118:121], v[34:49]
	s_nop 2
	s_waitcnt lgkmcnt(0)
	v_mfma_f32_32x32x16_bf16 v[34:49], v[102:105], v[114:117], v[34:49]
	s_nop 10
	s_setprio 1
	v_exp_f32_e32 v99, v66
	v_exp_f32_e32 v100, v67
	v_exp_f32_e32 v101, v68
	v_exp_f32_e32 v102, v69
	v_exp_f32_e32 v103, v70
	v_exp_f32_e32 v104, v71
	v_exp_f32_e32 v105, v72
	v_exp_f32_e32 v106, v73
	v_exp_f32_e32 v74, v74
	v_exp_f32_e32 v75, v75
	v_exp_f32_e32 v76, v76
	v_exp_f32_e32 v77, v77
	v_exp_f32_e32 v78, v78
	v_exp_f32_e32 v79, v79
	v_add3_u32 v70, s0, v189, v205
	v_exp_f32_e32 v80, v80
	v_add_u32_e32 v109, 0x6800, v70
	v_exp_f32_e32 v81, v81
	ds_read_b128 v[66:69], v109
	v_add_u32_e32 v112, 0x8900, v70
	v_exp_f32_e32 v82, v82
	v_exp_f32_e32 v83, v83
	v_exp_f32_e32 v84, v84
	v_exp_f32_e32 v85, v85
	v_exp_f32_e32 v86, v86
	v_exp_f32_e32 v87, v87
	v_exp_f32_e32 v88, v88
	v_exp_f32_e32 v89, v89
	ds_read_b128 v[70:73], v112 offset:256
	v_exp_f32_e32 v107, v50
	v_exp_f32_e32 v108, v51
	v_exp_f32_e32 v110, v52
	v_mov_b32_e32 v111, v53
	v_cvt_pk_bf16_f32 v50, v82, v83
	v_cvt_pk_bf16_f32 v51, v84, v85
	v_cvt_pk_bf16_f32 v52, v86, v87
	v_cvt_pk_bf16_f32 v53, v88, v89
	v_exp_f32_e32 v113, v54
	s_waitcnt lgkmcnt(1)
	v_mfma_f32_32x32x16_bf16 v[18:33], v[66:69], v[50:53], v[18:33]
	ds_read_b128 v[66:69], v109 offset:32
	v_exp_f32_e32 v114, v55
	v_exp_f32_e32 v90, v90
	v_exp_f32_e32 v91, v91
	v_exp_f32_e32 v92, v92
	v_exp_f32_e32 v93, v93
	v_exp_f32_e32 v94, v94
	v_exp_f32_e32 v95, v95
	v_exp_f32_e32 v96, v96
	v_exp_f32_e32 v97, v97
	s_waitcnt lgkmcnt(1)
	v_mfma_f32_32x32x16_bf16 v[2:17], v[70:73], v[50:53], v[2:17]
	v_exp_f32_e32 v70, v56
	v_mov_b32_e32 v71, v57
	ds_read_b128 v[54:57], v112 offset:288
	v_cvt_pk_bf16_f32 v50, v90, v91
	v_cvt_pk_bf16_f32 v51, v92, v93
	v_cvt_pk_bf16_f32 v52, v94, v95
	v_cvt_pk_bf16_f32 v53, v96, v97
	v_exp_f32_e32 v72, v58
	s_waitcnt lgkmcnt(1)
	v_mfma_f32_32x32x16_bf16 v[18:33], v[66:69], v[50:53], v[18:33]
	ds_read_b128 v[66:69], v109 offset:64
	v_exp_f32_e32 v73, v59
	v_exp_f32_e32 v115, v60
	v_exp_f32_e32 v111, v111
	s_waitcnt lgkmcnt(1)
	v_mfma_f32_32x32x16_bf16 v[2:17], v[54:57], v[50:53], v[2:17]
	ds_read_b128 v[54:57], v112 offset:320
	v_cvt_pk_bf16_f32 v50, v99, v100
	v_cvt_pk_bf16_f32 v51, v101, v102
	v_cvt_pk_bf16_f32 v52, v103, v104
	v_cvt_pk_bf16_f32 v53, v105, v106
	v_exp_f32_e32 v71, v71
	s_waitcnt lgkmcnt(1)
	v_mfma_f32_32x32x16_bf16 v[18:33], v[66:69], v[50:53], v[18:33]
	v_exp_f32_e32 v66, v61
	v_exp_f32_e32 v62, v62
	v_exp_f32_e32 v63, v63
	ds_read_b128 v[58:61], v109 offset:96
	v_exp_f32_e32 v67, v34
	s_waitcnt lgkmcnt(1)
	v_mfma_f32_32x32x16_bf16 v[2:17], v[54:57], v[50:53], v[2:17]
	ds_read_b128 v[54:57], v112 offset:352
	v_cvt_pk_bf16_f32 v50, v74, v75
	v_cvt_pk_bf16_f32 v51, v76, v77
	v_cvt_pk_bf16_f32 v52, v78, v79
	v_cvt_pk_bf16_f32 v53, v80, v81
	v_exp_f32_e32 v68, v35
	s_waitcnt lgkmcnt(1)
	v_mfma_f32_32x32x16_bf16 v[18:33], v[58:61], v[50:53], v[18:33]
	ds_read_b128 v[58:61], v109 offset:128
	v_exp_f32_e32 v69, v36
	v_cvt_pk_bf16_f32 v34, v107, v108
	v_cvt_pk_bf16_f32 v35, v110, v111
	v_cvt_pk_bf16_f32 v36, v113, v114
	s_waitcnt lgkmcnt(1)
	v_mfma_f32_32x32x16_bf16 v[2:17], v[54:57], v[50:53], v[2:17]
	ds_read_b128 v[50:53], v112 offset:384
	v_mov_b32_e32 v54, v37
	v_cvt_pk_bf16_f32 v37, v70, v71
	v_exp_f32_e32 v64, v64
	v_exp_f32_e32 v65, v65
	s_waitcnt lgkmcnt(1)
	v_mfma_f32_32x32x16_bf16 v[18:33], v[58:61], v[34:37], v[18:33]
	v_exp_f32_e32 v58, v54
	v_exp_f32_e32 v59, v38
	ds_read_b128 v[54:57], v109 offset:160
	v_exp_f32_e32 v60, v39
	v_exp_f32_e32 v61, v40
	s_waitcnt lgkmcnt(1)
	v_mfma_f32_32x32x16_bf16 v[2:17], v[50:53], v[34:37], v[2:17]
	v_mov_b32_e32 v50, v41
	ds_read_b128 v[38:41], v112 offset:416
	v_cvt_pk_bf16_f32 v34, v72, v73
	v_cvt_pk_bf16_f32 v35, v115, v66
	v_cvt_pk_bf16_f32 v36, v62, v63
	v_cvt_pk_bf16_f32 v37, v64, v65
	s_waitcnt lgkmcnt(1)
	s_nop 0
	v_mfma_f32_32x32x16_bf16 v[18:33], v[54:57], v[34:37], v[18:33]
	v_exp_f32_e32 v54, v50
	ds_read_b128 v[50:53], v109 offset:192
	v_exp_f32_e32 v55, v42
	v_exp_f32_e32 v56, v43
	v_exp_f32_e32 v57, v44
	s_waitcnt lgkmcnt(1)
	v_mfma_f32_32x32x16_bf16 v[2:17], v[38:41], v[34:37], v[2:17]
	ds_read_b128 v[38:41], v112 offset:448
	v_cvt_pk_bf16_f32 v34, v67, v68
	v_cvt_pk_bf16_f32 v35, v69, v58
	v_cvt_pk_bf16_f32 v36, v59, v60
	v_cvt_pk_bf16_f32 v37, v61, v54
	v_exp_f32_e32 v48, v48
	s_lshl_b64 s[10:11], s[10:11], 10
	s_waitcnt lgkmcnt(1)
	v_mfma_f32_32x32x16_bf16 v[18:33], v[50:53], v[34:37], v[18:33]
	v_exp_f32_e32 v50, v45
	v_exp_f32_e32 v46, v46
	v_exp_f32_e32 v47, v47
	ds_read_b128 v[42:45], v109 offset:224
	s_add_u32 s0, s36, s10
	s_waitcnt lgkmcnt(1)
	v_mfma_f32_32x32x16_bf16 v[2:17], v[38:41], v[34:37], v[2:17]
	ds_read_b128 v[38:41], v112 offset:480
	v_exp_f32_e32 v49, v49
	v_cvt_pk_bf16_f32 v34, v55, v56
	v_cvt_pk_bf16_f32 v35, v57, v50
	v_cvt_pk_bf16_f32 v36, v46, v47
	v_cvt_pk_bf16_f32 v37, v48, v49
	s_addc_u32 s11, s37, s11
	s_lshl_b32 s10, s49, 7
	s_waitcnt lgkmcnt(1)
	v_mfma_f32_32x32x16_bf16 v[18:33], v[42:45], v[34:37], v[18:33]
	s_add_u32 s10, s0, s10
	s_addc_u32 s11, s11, 0
	s_waitcnt lgkmcnt(0)
	s_barrier
	v_mfma_f32_32x32x16_bf16 v[2:17], v[38:41], v[34:37], v[2:17]
	s_branch .Lmla_fin_join
.Lmfb_final:
	s_setprio 0
	v_add_f32_e32 v1, v1, v239
	v_add3_u32 v133, s0, v132, v204
	ds_read_b128 v[34:37], v133
	ds_read_b128 v[122:125], v133 offset:32
	s_waitcnt lgkmcnt(1)
	v_mfma_f32_32x32x16_bf16 v[82:97], v[34:37], v[102:105], 0
	ds_read_b128 v[34:37], v133 offset:6656
	ds_read_b128 v[126:129], v133 offset:6688
	s_waitcnt lgkmcnt(1)
	v_mfma_f32_32x32x16_bf16 v[66:81], v[34:37], v[102:105], 0
	ds_read_b128 v[34:37], v133 offset:13312
	ds_read_b128 v[174:177], v133 offset:13344
	s_waitcnt lgkmcnt(1)
	v_mfma_f32_32x32x16_bf16 v[50:65], v[34:37], v[102:105], 0
	ds_read_b128 v[34:37], v133 offset:19968
	ds_read_b128 v[178:181], v133 offset:20000
	s_waitcnt lgkmcnt(1)
	v_mfma_f32_32x32x16_bf16 v[34:49], v[34:37], v[102:105], 0
	v_mfma_f32_32x32x16_bf16 v[82:97], v[122:125], v[110:113], v[82:97]
	v_mfma_f32_32x32x16_bf16 v[66:81], v[126:129], v[110:113], v[66:81]
	v_mfma_f32_32x32x16_bf16 v[50:65], v[174:177], v[110:113], v[50:65]
	s_waitcnt lgkmcnt(0)
	v_mfma_f32_32x32x16_bf16 v[34:49], v[178:181], v[110:113], v[34:49]
	ds_read_b128 v[102:105], v133 offset:64
	ds_read_b128 v[110:113], v133 offset:96
	s_waitcnt lgkmcnt(1)
	v_mfma_f32_32x32x16_bf16 v[82:97], v[102:105], v[98:101], v[82:97]
	ds_read_b128 v[102:105], v133 offset:6720
	ds_read_b128 v[122:125], v133 offset:6752
	s_waitcnt lgkmcnt(1)
	v_mfma_f32_32x32x16_bf16 v[66:81], v[102:105], v[98:101], v[66:81]
	ds_read_b128 v[102:105], v133 offset:13376
	ds_read_b128 v[126:129], v133 offset:13408
	s_waitcnt lgkmcnt(1)
	v_mfma_f32_32x32x16_bf16 v[50:65], v[102:105], v[98:101], v[50:65]
	ds_read_b128 v[102:105], v133 offset:20032
	ds_read_b128 v[174:177], v133 offset:20064
	v_mfma_f32_32x32x16_bf16 v[82:97], v[110:113], v[106:109], v[82:97]
	s_waitcnt lgkmcnt(1)
	v_mfma_f32_32x32x16_bf16 v[34:49], v[102:105], v[98:101], v[34:49]
	ds_read_b128 v[98:101], v133 offset:128
	ds_read_b128 v[102:105], v133 offset:160
	v_mfma_f32_32x32x16_bf16 v[66:81], v[122:125], v[106:109], v[66:81]
	s_waitcnt lgkmcnt(1)
	v_mfma_f32_32x32x16_bf16 v[82:97], v[98:101], v[118:121], v[82:97]
	v_mfma_f32_32x32x16_bf16 v[50:65], v[126:129], v[106:109], v[50:65]
	v_mfma_f32_32x32x16_bf16 v[34:49], v[174:177], v[106:109], v[34:49]
	ds_read_b128 v[98:101], v133 offset:6784
	ds_read_b128 v[106:109], v133 offset:6816
	s_waitcnt lgkmcnt(1)
	v_mfma_f32_32x32x16_bf16 v[66:81], v[98:101], v[118:121], v[66:81]
	ds_read_b128 v[98:101], v133 offset:13440
	ds_read_b128 v[110:113], v133 offset:13472
	v_mfma_f32_32x32x16_bf16 v[82:97], v[102:105], v[114:117], v[82:97]
	s_waitcnt lgkmcnt(1)
	v_mfma_f32_32x32x16_bf16 v[50:65], v[98:101], v[118:121], v[50:65]
	s_nop 9
	ds_read_b128 v[98:101], v133 offset:20096
	ds_read_b128 v[102:105], v133 offset:20128
	v_mfma_f32_32x32x16_bf16 v[66:81], v[106:109], v[114:117], v[66:81]
	s_nop 6
	s_waitcnt lgkmcnt(2)
	v_mfma_f32_32x32x16_bf16 v[50:65], v[110:113], v[114:117], v[50:65]
	s_waitcnt lgkmcnt(1)
	v_mfma_f32_32x32x16_bf16 v[34:49], v[98:101], v[118:121], v[34:49]
	s_nop 2
	s_waitcnt lgkmcnt(0)
	v_mfma_f32_32x32x16_bf16 v[34:49], v[102:105], v[114:117], v[34:49]
	s_nop 10
	s_barrier
	s_setprio 1
	v_exp_f32_e32 v99, v66
	v_exp_f32_e32 v100, v67
	v_exp_f32_e32 v101, v68
	v_exp_f32_e32 v102, v69
	v_exp_f32_e32 v103, v70
	v_exp_f32_e32 v104, v71
	v_exp_f32_e32 v105, v72
	v_exp_f32_e32 v106, v73
	v_exp_f32_e32 v74, v74
	v_exp_f32_e32 v75, v75
	v_exp_f32_e32 v76, v76
	v_exp_f32_e32 v77, v77
	v_exp_f32_e32 v78, v78
	v_exp_f32_e32 v79, v79
	v_add3_u32 v70, s0, v189, v205
	v_exp_f32_e32 v80, v80
	v_add_u32_e32 v109, 0x6800, v70
	v_exp_f32_e32 v81, v81
	ds_read_b128 v[66:69], v109
	v_add_u32_e32 v112, 0x8900, v70
	v_exp_f32_e32 v82, v82
	v_exp_f32_e32 v83, v83
	v_exp_f32_e32 v84, v84
	v_exp_f32_e32 v85, v85
	v_exp_f32_e32 v86, v86
	v_exp_f32_e32 v87, v87
	v_exp_f32_e32 v88, v88
	v_exp_f32_e32 v89, v89
	ds_read_b128 v[70:73], v112 offset:256
	v_exp_f32_e32 v107, v50
	v_exp_f32_e32 v108, v51
	v_exp_f32_e32 v110, v52
	v_mov_b32_e32 v111, v53
	v_cvt_pk_bf16_f32 v50, v82, v83
	v_cvt_pk_bf16_f32 v51, v84, v85
	v_cvt_pk_bf16_f32 v52, v86, v87
	v_cvt_pk_bf16_f32 v53, v88, v89
	v_exp_f32_e32 v113, v54
	s_waitcnt lgkmcnt(1)
	v_mfma_f32_32x32x16_bf16 v[18:33], v[66:69], v[50:53], v[18:33]
	ds_read_b128 v[66:69], v109 offset:32
	v_exp_f32_e32 v114, v55
	v_exp_f32_e32 v90, v90
	v_exp_f32_e32 v91, v91
	v_exp_f32_e32 v92, v92
	v_exp_f32_e32 v93, v93
	v_exp_f32_e32 v94, v94
	v_exp_f32_e32 v95, v95
	v_exp_f32_e32 v96, v96
	v_exp_f32_e32 v97, v97
	s_waitcnt lgkmcnt(1)
	v_mfma_f32_32x32x16_bf16 v[2:17], v[70:73], v[50:53], v[2:17]
	v_exp_f32_e32 v70, v56
	v_mov_b32_e32 v71, v57
	ds_read_b128 v[54:57], v112 offset:288
	v_cvt_pk_bf16_f32 v50, v90, v91
	v_cvt_pk_bf16_f32 v51, v92, v93
	v_cvt_pk_bf16_f32 v52, v94, v95
	v_cvt_pk_bf16_f32 v53, v96, v97
	v_exp_f32_e32 v72, v58
	s_waitcnt lgkmcnt(1)
	v_mfma_f32_32x32x16_bf16 v[18:33], v[66:69], v[50:53], v[18:33]
	ds_read_b128 v[66:69], v109 offset:64
	v_exp_f32_e32 v73, v59
	v_exp_f32_e32 v115, v60
	v_exp_f32_e32 v111, v111
	s_waitcnt lgkmcnt(1)
	v_mfma_f32_32x32x16_bf16 v[2:17], v[54:57], v[50:53], v[2:17]
	ds_read_b128 v[54:57], v112 offset:320
	v_cvt_pk_bf16_f32 v50, v99, v100
	v_cvt_pk_bf16_f32 v51, v101, v102
	v_cvt_pk_bf16_f32 v52, v103, v104
	v_cvt_pk_bf16_f32 v53, v105, v106
	v_exp_f32_e32 v71, v71
	s_waitcnt lgkmcnt(1)
	v_mfma_f32_32x32x16_bf16 v[18:33], v[66:69], v[50:53], v[18:33]
	v_exp_f32_e32 v66, v61
	v_exp_f32_e32 v62, v62
	v_exp_f32_e32 v63, v63
	ds_read_b128 v[58:61], v109 offset:96
	v_exp_f32_e32 v67, v34
	s_waitcnt lgkmcnt(1)
	v_mfma_f32_32x32x16_bf16 v[2:17], v[54:57], v[50:53], v[2:17]
	ds_read_b128 v[54:57], v112 offset:352
	v_cvt_pk_bf16_f32 v50, v74, v75
	v_cvt_pk_bf16_f32 v51, v76, v77
	v_cvt_pk_bf16_f32 v52, v78, v79
	v_cvt_pk_bf16_f32 v53, v80, v81
	v_exp_f32_e32 v68, v35
	s_waitcnt lgkmcnt(1)
	v_mfma_f32_32x32x16_bf16 v[18:33], v[58:61], v[50:53], v[18:33]
	ds_read_b128 v[58:61], v109 offset:128
	v_exp_f32_e32 v69, v36
	v_cvt_pk_bf16_f32 v34, v107, v108
	v_cvt_pk_bf16_f32 v35, v110, v111
	v_cvt_pk_bf16_f32 v36, v113, v114
	s_waitcnt lgkmcnt(1)
	v_mfma_f32_32x32x16_bf16 v[2:17], v[54:57], v[50:53], v[2:17]
	ds_read_b128 v[50:53], v112 offset:384
	v_mov_b32_e32 v54, v37
	v_cvt_pk_bf16_f32 v37, v70, v71
	v_exp_f32_e32 v64, v64
	v_exp_f32_e32 v65, v65
	s_waitcnt lgkmcnt(1)
	v_mfma_f32_32x32x16_bf16 v[18:33], v[58:61], v[34:37], v[18:33]
	v_exp_f32_e32 v58, v54
	v_exp_f32_e32 v59, v38
	ds_read_b128 v[54:57], v109 offset:160
	v_exp_f32_e32 v60, v39
	v_exp_f32_e32 v61, v40
	s_waitcnt lgkmcnt(1)
	v_mfma_f32_32x32x16_bf16 v[2:17], v[50:53], v[34:37], v[2:17]
	v_mov_b32_e32 v50, v41
	ds_read_b128 v[38:41], v112 offset:416
	v_cvt_pk_bf16_f32 v34, v72, v73
	v_cvt_pk_bf16_f32 v35, v115, v66
	v_cvt_pk_bf16_f32 v36, v62, v63
	v_cvt_pk_bf16_f32 v37, v64, v65
	s_waitcnt lgkmcnt(1)
	s_nop 0
	v_mfma_f32_32x32x16_bf16 v[18:33], v[54:57], v[34:37], v[18:33]
	v_exp_f32_e32 v54, v50
	ds_read_b128 v[50:53], v109 offset:192
	v_exp_f32_e32 v55, v42
	v_exp_f32_e32 v56, v43
	v_exp_f32_e32 v57, v44
	s_waitcnt lgkmcnt(1)
	v_mfma_f32_32x32x16_bf16 v[2:17], v[38:41], v[34:37], v[2:17]
	ds_read_b128 v[38:41], v112 offset:448
	v_cvt_pk_bf16_f32 v34, v67, v68
	v_cvt_pk_bf16_f32 v35, v69, v58
	v_cvt_pk_bf16_f32 v36, v59, v60
	v_cvt_pk_bf16_f32 v37, v61, v54
	v_exp_f32_e32 v48, v48
	s_lshl_b64 s[10:11], s[10:11], 10
	s_waitcnt lgkmcnt(1)
	v_mfma_f32_32x32x16_bf16 v[18:33], v[50:53], v[34:37], v[18:33]
	v_exp_f32_e32 v50, v45
	v_exp_f32_e32 v46, v46
	v_exp_f32_e32 v47, v47
	ds_read_b128 v[42:45], v109 offset:224
	s_add_u32 s0, s36, s10
	s_waitcnt lgkmcnt(1)
	v_mfma_f32_32x32x16_bf16 v[2:17], v[38:41], v[34:37], v[2:17]
	ds_read_b128 v[38:41], v112 offset:480
	v_exp_f32_e32 v49, v49
	v_cvt_pk_bf16_f32 v34, v55, v56
	v_cvt_pk_bf16_f32 v35, v57, v50
	v_cvt_pk_bf16_f32 v36, v46, v47
	v_cvt_pk_bf16_f32 v37, v48, v49
	s_addc_u32 s11, s37, s11
	s_lshl_b32 s10, s49, 7
	s_waitcnt lgkmcnt(1)
	v_mfma_f32_32x32x16_bf16 v[18:33], v[42:45], v[34:37], v[18:33]
	s_add_u32 s10, s0, s10
	s_addc_u32 s11, s11, 0
	s_waitcnt lgkmcnt(0)
	v_mfma_f32_32x32x16_bf16 v[2:17], v[38:41], v[34:37], v[2:17]
	s_branch .Lmla_fin_join
